# E17a: norm2 row loop only: w/sc/sh loads issued up-front before next-row prefetch
# speedup vs baseline: 1.0042x; 1.0042x over previous
; __device__ __forceinline__ void norm_phase(float* __restrict__ X, bf16_t* __restrict__ H, const float* __restrict__ nw, const float* __restrict__ modL, const float* __restrict__ modC, int sh_off, int sc_off, ...
;     ...
;   if (r < T_TOK) { const float* sp = NSRC(r);
; #pragma unroll
;     for (int i = 0; i < 4; ++i) nx[i] = *(const f32x4*)(sp + i * 256 + lane * 4);
;   }
;   for (; r < T_TOK; r += stride) {
;     float* xr = X + (size_t)r * DM; f32x4 v[4]; float ss = 0.f;
; #pragma unroll
;     for (int i = 0; i < 4; ++i) v[i] = nx[i];
;     const int rn = r + stride;
;     if (rn < T_TOK) { const float* sp = NSRC(rn);
; #pragma unroll
;       for (int i = 0; i < 4; ++i) nx[i] = *(const f32x4*)(sp + i * 256 + lane * 4);
;     }
;     if (r < NCTX && nsl > 0) {
;       for (int sl = 0; sl < nsl; ++sl) { const float* pr = part + ((size_t)sl * NCTX + r) * DM;
; #pragma unroll
;         for (int i = 0; i < 4; ++i) v[i] += *(const f32x4*)(pr + i * 256 + lane * 4); }
; #pragma unroll
;       for (int i = 0; i < 4; ++i) *(f32x4*)(xr + i * 256 + lane * 4) = v[i];
;     }
; #pragma unroll
;     for (int i = 0; i < 4; ++i) ss += v[i][0] * v[i][0] + v[i][1] * v[i][1] + v[i][2] * v[i][2] + v[i][3] * v[i][3];
;     ss = wave_sum(ss); const float rstd = rsqrtf(ss * (1.f / DM) + EPSN);
.LBB0_2699:
	s_or_b64 exec, exec, s[24:25]
	v_lshlrev_b32_e32 v2, 2, v6
	v_and_b32_e32 v36, 0xfc, v2
	s_lshl_b64 s[24:25], s[34:35], 12
	v_lshlrev_b32_e32 v12, 2, v36
	v_mov_b32_e32 v13, v144
	s_waitcnt lgkmcnt(0)
	s_add_u32 s22, s22, s24
	v_lshl_add_u64 v[0:1], v[0:1], 0, v[12:13]
	s_addc_u32 s23, s23, s25
	global_load_dwordx4 v[32:35], v[0:1], off
	global_load_dwordx4 v[28:31], v[0:1], off offset:1024
	global_load_dwordx4 v[24:27], v[0:1], off offset:2048
	global_load_dwordx4 v[8:11], v[0:1], off offset:3072
	s_nop 0
	global_load_dwordx4 v[0:3], v12, s[22:23]
	v_readlane_b32 s24, v255, 30
	v_readlane_b32 s25, v255, 31
	s_lshl_b64 s[24:25], s[24:25], 2
	s_add_u32 s18, s18, s24
	s_addc_u32 s19, s19, s25
	s_add_u32 s26, s18, 0x9b90000
	s_addc_u32 s27, s19, 0
	s_lshl_b64 s[18:19], s[4:5], 2
	s_add_u32 s16, s16, s18
	s_addc_u32 s17, s17, s19
	s_add_u32 s28, s16, 0x9b90000
	v_lshl_add_u64 v[38:39], s[22:23], 0, v[12:13]
	v_and_b32_e32 v13, 63, v6
	v_lshlrev_b64 v[6:7], 11, v[56:57]
	s_addc_u32 s29, s17, 0
	v_lshl_or_b32 v6, v13, 3, v6
	s_cmp_lg_u64 s[14:15], 0
	v_or_b32_e32 v12, 0x100, v36
	v_or_b32_e32 v14, 0x200, v36
	v_or_b32_e32 v16, 0x300, v36
	v_lshl_add_u64 v[6:7], s[8:9], 0, v[6:7]
	s_mov_b64 s[8:9], 0x4100000
	s_mov_b64 s[16:17], 0
	s_cselect_b64 s[18:19], -1, 0
	v_lshlrev_b32_e32 v40, 4, v13
	v_mov_b32_e32 v41, v144
	v_lshl_add_u64 v[42:43], s[20:21], 0, v[4:5]
	v_lshl_add_u64 v[44:45], v[6:7], 0, s[8:9]
	v_lshl_add_u64 v[46:47], s[10:11], 0, v[4:5]
	v_lshlrev_b32_e32 v48, 2, v12
	v_lshlrev_b32_e32 v50, 2, v14
	v_lshlrev_b32_e32 v52, 2, v16
	s_waitcnt vmcnt(1)
	s_branch .LBB0_2701
.LBB0_2700:
	s_or_b64 exec, exec, s[20:21]
	v_mul_f32_e32 v37, v33, v33
	v_mul_f32_e32 v49, v29, v29
	v_mul_f32_e32 v51, v25, v25
	v_fmac_f32_e32 v37, v32, v32
	v_fmac_f32_e32 v49, v28, v28
	v_mul_f32_e32 v53, v9, v9
	v_fmac_f32_e32 v51, v24, v24
	v_fmac_f32_e32 v37, v34, v34
	v_fmac_f32_e32 v49, v30, v30
	v_fmac_f32_e32 v53, v8, v8
	v_fmac_f32_e32 v51, v26, v26
	v_fmac_f32_e32 v37, v35, v35
	v_fmac_f32_e32 v49, v31, v31
	v_fmac_f32_e32 v53, v10, v10
	v_fmac_f32_e32 v51, v27, v27
	v_add_f32_e32 v37, v37, v49
	v_fmac_f32_e32 v53, v11, v11
	v_add_f32_e32 v37, v51, v37
	v_add_f32_e32 v37, v53, v37
	v_readlane_b32 s8, v255, 9
	v_readlane_b32 s9, v255, 10
	v_add_f32_dpp v37, v37, v37 quad_perm:[1,0,3,2] row_mask:0xf bank_mask:0xf bound_ctrl:1
	v_lshl_add_u64 v[42:43], v[42:43], 0, s[68:69]
	v_lshl_add_u64 v[46:47], v[46:47], 0, s[68:69]
	v_add_f32_dpp v37, v37, v37 quad_perm:[2,3,0,1] row_mask:0xf bank_mask:0xf bound_ctrl:1
	s_nop 1
	v_add_f32_dpp v37, v37, v37 row_ror:4 row_mask:0xf bank_mask:0xf bound_ctrl:1
	s_nop 1
	v_add_f32_dpp v37, v37, v37 row_ror:8 row_mask:0xf bank_mask:0xf bound_ctrl:1
	v_mov_b32_e32 v49, v37
	s_nop 1
	v_permlane16_swap_b32_e32 v37, v49
	v_add_f32_e32 v37, v37, v49
	v_mov_b32_e32 v49, v37
	s_nop 1
	v_permlane32_swap_b32_e32 v37, v49
	v_add_f32_e32 v37, v37, v49
	v_fmamk_f32 v37, v37, 0x3a800000, v186
	v_mul_f32_e32 v49, 0x4b800000, v37
	v_cmp_gt_f32_e32 vcc, s57, v37
	s_nop 1
	v_cndmask_b32_e32 v37, v37, v49, vcc
	v_rsq_f32_e32 v37, v37
	s_nop 0
	v_mul_f32_e32 v51, 0x45800000, v37
	v_cndmask_b32_e32 v37, v37, v51, vcc
	s_cmp_lg_u32 s32, 0
	s_cbranch_scc1 .Lnrm_pf_n2
	s_waitcnt vmcnt(0)
; __device__ __forceinline__ void store_bf16x4(bf16_t* p, f32x4 v) { u32x2 w; w.x = cvt_pk_bf16(v[0], v[1]); w.y = cvt_pk_bf16(v[2], v[3]); *(u32x2*)p = w; }
; __device__ __forceinline__ void norm_phase(float* __restrict__ X, bf16_t* __restrict__ H, const float* __restrict__ nw, const float* __restrict__ modL, const float* __restrict__ modC, int sh_off, int sc_off, ...
;     ...
;     const int rn = r + stride;
;     if (rn < T_TOK) { const float* sp = NSRC(rn);
; #pragma unroll
;       for (int i = 0; i < 4; ++i) nx[i] = *(const f32x4*)(sp + i * 256 + lane * 4);
;     }
;     if (r < NCTX && nsl > 0) {
;       for (int sl = 0; sl < nsl; ++sl) { const float* pr = part + ((size_t)sl * NCTX + r) * DM;
; #pragma unroll
;         for (int i = 0; i < 4; ++i) v[i] += *(const f32x4*)(pr + i * 256 + lane * 4); }
; #pragma unroll
;       for (int i = 0; i < 4; ++i) *(f32x4*)(xr + i * 256 + lane * 4) = v[i];
;     }
; #pragma unroll
;     for (int i = 0; i < 4; ++i) ss += v[i][0] * v[i][0] + v[i][1] * v[i][1] + v[i][2] * v[i][2] + v[i][3] * v[i][3];
;     ss = wave_sum(ss); const float rstd = rsqrtf(ss * (1.f / DM) + EPSN);
;     const float* md = r < NCTX ? modC : modL;
; #pragma unroll
;     for (int i = 0; i < 4; ++i) { const int col = i * 256 + lane * 4; const f32x4 w = *(const f32x4*)(nw + col), sc = *(const f32x4*)(md + sc_off + col), sh = *(const f32x4*)(md + sh_off + col);
;       f32x4 h; for (int j = 0; j < 4; ++j) h[j] = (v[i][j] * rstd) * w[j] * (1.f + sc[j]) + sh[j];
;       store_bf16x4(H + (size_t)r * DM + col, h); }
.Lnrm_pf_n2:
	s_waitcnt vmcnt(4)
	v_mul_f32_e32 v32, v32, v37
	v_mul_f32_e32 v33, v33, v37
	v_mul_f32_e32 v34, v34, v37
	v_mul_f32_e32 v35, v35, v37
	v_mul_f32_e32 v32, v0, v32
	v_mul_f32_e32 v33, v1, v33
	v_mul_f32_e32 v34, v2, v34
	v_mul_f32_e32 v35, v3, v35
	v_add_f32_e32 v162, 1.0, v162
	v_add_f32_e32 v163, 1.0, v163
	v_add_f32_e32 v164, 1.0, v164
	v_add_f32_e32 v165, 1.0, v165
	v_fma_f32 v32, v162, v32, v178
	v_fma_f32 v33, v163, v33, v179
	v_fma_f32 v34, v164, v34, v180
	v_fma_f32 v35, v165, v35, v181
	v_cvt_pk_bf16_f32 v60, v32, v33
	v_cvt_pk_bf16_f32 v61, v34, v35
	global_store_dwordx2 v[44:45], v[60:61], off
	v_mul_f32_e32 v28, v28, v37
	v_mul_f32_e32 v29, v29, v37
	v_mul_f32_e32 v30, v30, v37
	v_mul_f32_e32 v31, v31, v37
	v_mul_f32_e32 v28, v150, v28
	v_mul_f32_e32 v29, v151, v29
	v_mul_f32_e32 v30, v152, v30
	v_mul_f32_e32 v31, v153, v31
	v_add_f32_e32 v166, 1.0, v166
	v_add_f32_e32 v167, 1.0, v167
	v_add_f32_e32 v168, 1.0, v168
	v_add_f32_e32 v169, 1.0, v169
	v_fma_f32 v28, v166, v28, v182
	v_fma_f32 v29, v167, v29, v183
	v_fma_f32 v30, v168, v30, v184
	v_fma_f32 v31, v169, v31, v185
	v_cvt_pk_bf16_f32 v62, v28, v29
	v_cvt_pk_bf16_f32 v63, v30, v31
	global_store_dwordx2 v[44:45], v[62:63], off offset:512
	v_mul_f32_e32 v24, v24, v37
	v_mul_f32_e32 v25, v25, v37
	v_mul_f32_e32 v26, v26, v37
	v_mul_f32_e32 v27, v27, v37
	v_mul_f32_e32 v24, v154, v24
	v_mul_f32_e32 v25, v155, v25
	v_mul_f32_e32 v26, v156, v26
	v_mul_f32_e32 v27, v157, v27
	v_add_f32_e32 v170, 1.0, v170
	v_add_f32_e32 v171, 1.0, v171
	v_add_f32_e32 v172, 1.0, v172
	v_add_f32_e32 v173, 1.0, v173
	v_fma_f32 v24, v170, v24, v214
	v_fma_f32 v25, v171, v25, v215
	v_fma_f32 v26, v172, v26, v216
	v_fma_f32 v27, v173, v27, v217
	v_cvt_pk_bf16_f32 v64, v24, v25
	v_cvt_pk_bf16_f32 v65, v26, v27
	global_store_dwordx2 v[44:45], v[64:65], off offset:1024
	v_mul_f32_e32 v8, v8, v37
	v_mul_f32_e32 v9, v9, v37
	v_mul_f32_e32 v10, v10, v37
	v_mul_f32_e32 v11, v11, v37
	v_mul_f32_e32 v8, v158, v8
	v_mul_f32_e32 v9, v159, v9
	v_mul_f32_e32 v10, v160, v10
	v_mul_f32_e32 v11, v161, v11
	v_add_f32_e32 v174, 1.0, v174
	v_add_f32_e32 v175, 1.0, v175
	v_add_f32_e32 v176, 1.0, v176
	v_add_f32_e32 v177, 1.0, v177
	v_fma_f32 v8, v174, v8, v218
	v_fma_f32 v9, v175, v9, v219
	v_fma_f32 v10, v176, v10, v220
	v_fma_f32 v11, v177, v11, v221
	v_cvt_pk_bf16_f32 v66, v8, v9
	v_cvt_pk_bf16_f32 v67, v10, v11
	global_store_dwordx2 v[44:45], v[66:67], off offset:1536
	s_waitcnt vmcnt(4)
	v_mov_b32_e32 v32, v20
	v_mov_b32_e32 v33, v21
	v_mov_b32_e32 v34, v22
	v_mov_b32_e32 v35, v23
	v_mov_b32_e32 v28, v16
	v_mov_b32_e32 v29, v17
	v_mov_b32_e32 v30, v18
	v_mov_b32_e32 v31, v19
	v_mov_b32_e32 v24, v12
	v_mov_b32_e32 v25, v13
	v_mov_b32_e32 v26, v14
	v_mov_b32_e32 v27, v15
	v_mov_b32_e32 v8, v4
	v_mov_b32_e32 v9, v5
	v_mov_b32_e32 v10, v6
	v_mov_b32_e32 v11, v7
	v_mov_b32_e32 v56, v54
	v_lshl_add_u64 v[44:45], v[44:45], 0, s[8:9]
	s_andn2_b64 exec, exec, s[16:17]
	s_cbranch_execz .LBB0_2712
.LBB0_2701:
	v_add_u32_e32 v54, s50, v56
	v_cmp_gt_i32_e32 vcc, s86, v54
	v_cmp_lt_i32_e64 s[8:9], s79, v54
	v_cmp_lt_i32_e64 s[22:23], s81, v56
	v_mov_b32_e32 v222, s29
	v_mov_b32_e32 v223, s27
	v_cndmask_b32_e64 v225, v222, v223, s[22:23]
	v_mov_b32_e32 v222, s28
	v_mov_b32_e32 v223, s26
	v_cndmask_b32_e64 v224, v222, v223, s[22:23]
	v_lshlrev_b32_e32 v226, 2, v36
	v_mov_b32_e32 v227, v144
	v_lshl_add_u64 v[224:225], v[224:225], 0, v[226:227]
	s_mov_b64 s[22:23], 0x4000
	v_lshl_add_u64 v[228:229], v[224:225], 0, s[22:23]
	s_mov_b64 s[22:23], 0x3000
	v_lshl_add_u64 v[230:231], v[224:225], 0, s[22:23]
	global_load_dwordx4 v[162:165], v[228:229], off
	global_load_dwordx4 v[178:181], v[230:231], off
	global_load_dwordx4 v[150:153], v[38:39], off offset:1024
	global_load_dwordx4 v[166:169], v[228:229], off offset:1024
	global_load_dwordx4 v[182:185], v[230:231], off offset:1024
	global_load_dwordx4 v[154:157], v[38:39], off offset:2048
	global_load_dwordx4 v[170:173], v[228:229], off offset:2048
	global_load_dwordx4 v[214:217], v[230:231], off offset:2048
	global_load_dwordx4 v[158:161], v[38:39], off offset:3072
	global_load_dwordx4 v[174:177], v[228:229], off offset:3072
	global_load_dwordx4 v[218:221], v[230:231], off offset:3072
	s_or_b32 s32, vcc_lo, vcc_hi
	s_and_saveexec_b64 s[20:21], vcc
	s_cbranch_execz .LBB0_2709
	v_cmp_lt_i32_e32 vcc, s81, v54
	s_and_saveexec_b64 s[22:23], vcc
	s_xor_b64 s[22:23], exec, s[22:23]
	v_mov_b32_e32 v55, v144
	v_lshlrev_b64 v[4:5], 12, v[54:55]
	v_lshl_add_u64 v[4:5], s[10:11], 0, v[4:5]
	s_andn2_saveexec_b64 s[22:23], s[22:23]
	s_cbranch_execz .LBB0_2708
	v_ashrrev_i32_e32 v55, 31, v54
	s_andn2_b64 vcc, exec, s[18:19]
	v_lshlrev_b64 v[6:7], 12, v[54:55]
	s_cbranch_vccnz .LBB0_2711
	v_lshl_add_u64 v[4:5], s[14:15], 0, v[6:7]
	s_cbranch_execnz .LBB0_2708
